# speedup vs baseline: 1.0089x; 1.0089x over previous
; __device__ __forceinline__ float ret_log_gamma(int h) { return log1pf(-exp2f(-5.0f - (float)h)); }
; #define IN_PH() (lo <= ph && ph < hi && opaque_tid(tid, tq))
; template <bool C3> __device__ __forceinline__ void ret_prefetch(RetPre& P, const bf16_t* proj, const float* cosT, const float* sinT, const bf16_t* KVT, int h, int n, int tid) {
; #pragma unroll
;     for (int it = 0; it < 2; ++it) { const int e = tid + it * NTHR, j = e & 127, c = e >> 7, tok = n * 128 + j; const bf16_t* rp = proj + (size_t)tok * LDP + h * 128 + 8 * c;
;         P.k1[it] = *(const u32x4*)(rp + C_CK); P.k2[it] = *(const u32x4*)(rp + C_CK + 64);
;         if (C3) { P.q1[it] = *(const u32x4*)(rp + C_CQ); P.q2[it] = *(const u32x4*)(rp + C_CQ + 64); }
;         }
; #pragma unroll
;     for (int it = 0; it < 4; ++it) { const int e = tid + it * NTHR, j = e >> 4, c = e & 15; P.v[it] = *(const u32x4*)(proj + (size_t)(n * 128 + j) * LDP + C_CV + h * 128 + 8 * c);
;         if (C3) P.pv[it] = *(const u32x4*)(KVT + (size_t)(h * 128 + n) * 16384 + j * 128 + 8 * c); }
; }
; __global__ void __launch_bounds__(NTHR, 2) mk_fwd(Args args_unused) {
;     ...
;         for (int rep = (DUP_MASK >> 3 & 1) ? 0 : 1; rep < 2; ++rep) if (IN_PH()) { PH_ENV(); const bool dummy = rep == 0;
;             int u = bid;
;             if (u < 1024) { RetPre P; ret_prefetch<true>(P, PROJ, cC, sC, KVT, u >> 7, u & 127, tq);
;                 for (;;) { const int h = u >> 7, n = u & 127; const float lg = ret_log_gamma(h); ret_stage<true>(lds, P, cC, sC, n, lg, tq);
;                     const int un = u + G; const bool hn = un < 1024; if (hn) ret_prefetch<true>(P, PROJ, cC, sC, KVT, un >> 7, un & 127, tq);
.LBB0_379:
	v_readlane_b32 s4, v253, 0
	s_cmp_le_i32 s4, s0
	v_readlane_b32 s5, v253, 1
	s_cselect_b64 s[8:9], -1, 0
	s_and_b64 s[4:5], s[8:9], s[6:7]
	s_andn2_b64 vcc, exec, s[4:5]
	s_cbranch_vccnz .LBB0_394
	v_readlane_b32 s4, v252, 26
	v_readlane_b32 s6, v253, 2
	v_readlane_b32 s5, v252, 27
	v_bfe_u32 v67, v202, 8, 1
	v_mul_u32_u24_e32 v67, 0xc0, v67
	v_xor_b32_e32 v67, v202, v67
	v_readlane_b32 s7, v253, 3
	s_and_b64 vcc, exec, s[4:5]
	s_cbranch_vccnz .LBB0_394
	s_load_dwordx2 s[4:5], s[6:7], 0x88
	s_nop 0
	s_load_dwordx2 s[6:7], s[6:7], 0x40
	v_and_b32_e32 v33, 0x7f, v67
	v_readlane_b32 s12, v254, 0
	v_writelane_b32 v252, s8, 52
	s_waitcnt lgkmcnt(0)
	s_add_u32 s24, s4, 0x10800000
	v_or_b32_e32 v0, s12, v33
	v_writelane_b32 v252, s9, 53
	v_mul_u32_u24_e32 v0, 0x3c00, v0
	s_addc_u32 s25, s5, 0
	v_lshlrev_b32_e32 v0, 1, v0
	v_mov_b32_e32 v1, v32
	v_readlane_b32 s14, v252, 4
	v_ashrrev_i32_e32 v134, 4, v67
	s_add_u32 s28, s4, 0x32ea0000
	v_lshl_add_u64 v[0:1], s[24:25], 0, v[0:1]
	v_readlane_b32 s15, v252, 5
	v_and_b32_e32 v114, -8, v134
	s_waitcnt vmcnt(4)
	v_add_u32_e32 v18, 0x200, v67
	s_addc_u32 s29, s5, 0
	v_lshl_add_u64 v[16:17], v[0:1], 0, s[14:15]
	v_ashrrev_i32_e32 v115, 31, v114
	v_ashrrev_i32_e32 v135, 4, v18
	s_add_u32 s30, s4, 0x332a0000
	v_readlane_b32 s8, v252, 22
	v_lshl_add_u64 v[0:1], v[114:115], 1, v[16:17]
	s_movk_i32 s10, 0x2000
	v_and_b32_e32 v116, -8, v135
	s_addc_u32 s31, s5, 0
	s_lshl_b32 s0, s8, 10
	v_add_co_u32_e32 v12, vcc, s10, v0
	v_ashrrev_i32_e32 v117, 31, v116
	v_readlane_b32 s9, v252, 23
	s_add_u32 s8, s4, 0x30d20000
	v_addc_co_u32_e32 v13, vcc, 0, v1, vcc
	v_lshl_add_u64 v[16:17], v[116:117], 1, v[16:17]
	s_addc_u32 s9, s5, 0
	v_add_co_u32_e32 v28, vcc, s10, v16
	v_lshlrev_b32_e32 v71, 3, v67
	v_readlane_b32 s10, v254, 1
	v_and_b32_e32 v66, 0x78, v71
	v_readlane_b32 s11, v254, 2
	s_add_u32 s10, s8, s10
	s_addc_u32 s11, s9, s11
	v_lshlrev_b32_e32 v68, 1, v66
	v_mov_b32_e32 v69, v32
	v_add_u32_e32 v34, s12, v134
	v_mov_b64_e32 v[60:61], s[24:25]
	v_lshl_add_u64 v[58:59], s[10:11], 0, v[68:69]
	v_mad_i64_i32 v[34:35], s[10:11], v34, s23, v[60:61]
	v_lshl_add_u64 v[34:35], v[34:35], 0, s[14:15]
	v_add_u32_e32 v42, s12, v135
	v_add_u32_e32 v50, 0x400, v67
	v_addc_co_u32_e32 v29, vcc, 0, v17, vcc
	v_lshl_add_u64 v[34:35], v[34:35], 0, v[68:69]
	s_movk_i32 s13, 0x3000
	v_mad_i64_i32 v[42:43], s[10:11], v42, s23, v[60:61]
	v_ashrrev_i32_e32 v136, 4, v50
	v_add_co_u32_e32 v34, vcc, s13, v34
	v_lshl_add_u64 v[42:43], v[42:43], 0, s[14:15]
	v_add_u32_e32 v50, s12, v136
	v_add_u32_e32 v62, 0x600, v67
	v_addc_co_u32_e32 v35, vcc, 0, v35, vcc
	v_lshl_add_u64 v[42:43], v[42:43], 0, v[68:69]
	v_mad_i64_i32 v[50:51], s[10:11], v50, s23, v[60:61]
	v_ashrrev_i32_e32 v137, 4, v62
	v_add_co_u32_e32 v42, vcc, s13, v42
	v_lshl_add_u64 v[50:51], v[50:51], 0, s[14:15]
	v_add_u32_e32 v62, s12, v137
	v_addc_co_u32_e32 v43, vcc, 0, v43, vcc
	v_lshl_add_u64 v[50:51], v[50:51], 0, v[68:69]
	v_mad_i64_i32 v[60:61], s[10:11], v62, s23, v[60:61]
	v_add_co_u32_e32 v50, vcc, s13, v50
	v_lshl_add_u64 v[60:61], v[60:61], 0, s[14:15]
	v_lshlrev_b32_e32 v118, 7, v134
	v_lshlrev_b32_e32 v120, 7, v135
	v_addc_co_u32_e32 v51, vcc, 0, v51, vcc
	v_lshlrev_b32_e32 v122, 7, v136
	v_lshl_add_u64 v[60:61], v[60:61], 0, v[68:69]
	v_lshlrev_b32_e32 v124, 7, v137
	global_load_dwordx4 v[0:3], v[12:13], off offset:3840
	global_load_dwordx4 v[4:7], v[12:13], off offset:3968
	global_load_dwordx4 v[8:11], v[12:13], off offset:1792
	s_nop 0
	global_load_dwordx4 v[12:15], v[12:13], off offset:1920
	s_nop 0
	global_load_dwordx4 v[16:19], v[28:29], off offset:3840
	global_load_dwordx4 v[20:23], v[28:29], off offset:3968
	global_load_dwordx4 v[24:27], v[28:29], off offset:1792
	s_nop 0
	global_load_dwordx4 v[28:31], v[28:29], off offset:1920
	v_ashrrev_i32_e32 v119, 31, v118
	v_ashrrev_i32_e32 v121, 31, v120
	v_ashrrev_i32_e32 v123, 31, v122
	v_add_co_u32_e32 v60, vcc, s13, v60
	v_ashrrev_i32_e32 v125, 31, v124
	v_lshl_add_u64 v[38:39], v[118:119], 1, v[58:59]
	v_lshl_add_u64 v[46:47], v[120:121], 1, v[58:59]
	v_lshl_add_u64 v[54:55], v[122:123], 1, v[58:59]
	v_addc_co_u32_e32 v61, vcc, 0, v61, vcc
	v_lshl_add_u64 v[62:63], v[124:125], 1, v[58:59]
	global_load_dwordx4 v[34:37], v[34:35], off offset:1792
	s_nop 0
	global_load_dwordx4 v[38:41], v[38:39], off
	s_nop 0
	global_load_dwordx4 v[42:45], v[42:43], off offset:1792
	s_nop 0
	global_load_dwordx4 v[46:49], v[46:47], off
	s_nop 0
	global_load_dwordx4 v[50:53], v[50:51], off offset:1792
	s_nop 0
	global_load_dwordx4 v[54:57], v[54:55], off
	s_nop 0
	global_load_dwordx4 v[58:61], v[60:61], off offset:1792
	s_nop 0
	global_load_dwordx4 v[62:65], v[62:63], off
	v_lshlrev_b32_e32 v70, 6, v67
	s_movk_i32 s10, 0x110
	v_and_b32_e32 v72, 0x1fc0, v70
	v_mad_u32_u24 v70, v33, s10, 0
	v_lshl_add_u64 v[126:127], s[8:9], 0, v[68:69]
	v_readlane_b32 s8, v252, 12
	v_readlane_b32 s9, v252, 13
	v_lshl_add_u32 v138, v114, 1, v70
	v_lshl_add_u32 v139, v116, 1, v70
	v_add_u32_e32 v69, s8, v68
; __device__ __forceinline__ void retc3_compute(LAS unsigned char* lds, const bf16_t* proj, bf16_t* outb, int out_ld, const float* cgn, float lg, int h, int n, int tid) {
;     LAS bf16_t* Qs = (LAS bf16_t*)(lds + C_T0); LAS bf16_t* Ks = (LAS bf16_t*)(lds + C_T1); LAS bf16_t* Vs = (LAS bf16_t*)(lds + C_T2); LAS bf16_t* Ps = (LAS bf16_t*)(lds + C_T3);
;     const int w = tid >> 6, lane = tid & 63, l15 = lane & 15, quad = lane >> 4;
;     const int i = 16 * w + l15;
;     const int tok = n * 128 + i;
;     const bf16_t* rowp = proj + (size_t)tok * LDP; bf16_t* orow = outb + (size_t)tok * out_ld;
;     bf16x8 qf[4];
; #pragma unroll
;     for (int kk = 0; kk < 4; ++kk) qf[kk] = *(const LAS bf16x8*)(Qs + i * CP + 32 * kk + quad * 8);
;     f32x4 acc[8];
;     const float qdec = __expf(lg * (float)(i + 1));
; #pragma unroll
;     for (int et = 0; et < 8; ++et) { f32x4 z = (f32x4){0.f, 0.f, 0.f, 0.f};
; #pragma unroll
;         for (int kk = 0; kk < 4; ++kk) { const bf16x8 a = *(const LAS bf16x8*)(Ps + (16 * et + l15) * CP + 32 * kk + quad * 8); z = mfma16(a, qf[kk], z); }
;         acc[et] = z * qdec; }
; #pragma unroll
;     for (int ks = 0; ks < 4; ++ks) {
;         if (2 * ks <= w) {
;             f32x4 s0 = (f32x4){0.f, 0.f, 0.f, 0.f}, s1 = (f32x4){0.f, 0.f, 0.f, 0.f};
; #pragma unroll
;             for (int kk = 0; kk < 4; ++kk) { const bf16x8 a0 = *(const LAS bf16x8*)(Ks + (32 * ks + l15) * CP + 32 * kk + quad * 8), a1 = *(const LAS bf16x8*)(Ks + (32 * ks + 16 + l15) * CP + 32 * kk + quad * 8);
;                 s0 = mfma16(a0, qf[kk], s0); s1 = mfma16(a1, qf[kk], s1); }
;             float p0[4], p1[4];
; #pragma unroll
;             for (int j = 0; j < 4; ++j) { const int d0 = i - (32 * ks + quad * 4 + j), d1 = d0 - 16;
;                 p0[j] = d0 >= 0 ? s0[j] * __expf(lg * (float)d0) : 0.f; p1[j] = d1 >= 0 ? s1[j] * __expf(lg * (float)d1) : 0.f; }
;             u32x4 pw; pw.x = cvt_pk_bf16(p0[0], p0[1]); pw.y = cvt_pk_bf16(p0[2], p0[3]); pw.z = cvt_pk_bf16(p1[0], p1[1]); pw.w = cvt_pk_bf16(p1[2], p1[3]);
;             const bf16x8 pb = __builtin_bit_cast(bf16x8, pw);
; #pragma unroll
;             for (int et = 0; et < 8; ++et) { const LAS bf16_t* vp = Vs + (32 * ks + quad * 4 + (l15 >> 2)) * CP + 16 * et + 4 * (l15 & 3);
;                 acc[et] = mfma16(cat44(lds_tr(vp), lds_tr(vp + 16 * CP)), pb, acc[et]); }
;         }
;     }
	v_add_u32_e32 v68, s9, v68
	v_mul_lo_u32 v70, v134, s10
	v_add_u32_e32 v140, v69, v70
	v_add_u32_e32 v141, v68, v70
	v_mul_lo_u32 v70, v135, s10
	v_add_u32_e32 v142, v69, v70
	v_add_u32_e32 v143, v68, v70
	v_mul_lo_u32 v70, v136, s10
	v_add_u32_e32 v144, v69, v70
	v_add_u32_e32 v145, v68, v70
	v_mul_lo_u32 v70, v137, s10
	v_add_u32_e32 v146, v69, v70
	v_add_u32_e32 v147, v68, v70
	v_ashrrev_i32_e32 v69, 6, v67
	v_and_b32_e32 v70, 15, v67
	v_bfe_u32 v73, v67, 4, 2
	v_lshl_or_b32 v148, v69, 4, v70
	v_mul_u32_u24_e32 v76, 0x110, v70
	v_lshlrev_b32_e32 v70, 2, v73
	v_bfe_u32 v67, v67, 2, 2
	v_or_b32_e32 v67, v70, v67
	v_and_b32_e32 v71, 24, v71
	v_mul_u32_u24_e32 v67, 0x110, v67
	v_add3_u32 v159, s8, v71, v67
	v_or_b32_e32 v67, 32, v70
	v_sub_u32_e32 v67, v148, v67
	v_add_u32_e32 v71, -16, v67
	v_cmp_lt_i32_e64 s[60:61], -1, v67
	v_cvt_f32_u32_e32 v160, v67
	v_cmp_lt_i32_e64 s[62:63], 15, v67
	v_or_b32_e32 v67, 33, v70
	v_sub_u32_e32 v67, v148, v67
	v_cvt_f32_u32_e32 v161, v71
	v_add_u32_e32 v71, -16, v67
	v_cmp_lt_i32_e64 s[64:65], -1, v67
	v_cvt_f32_u32_e32 v163, v67
	v_cmp_lt_i32_e64 s[66:67], 15, v67
	v_or_b32_e32 v67, 34, v70
	v_sub_u32_e32 v67, v148, v67
	v_cvt_f32_u32_e32 v171, v71
	v_add_u32_e32 v71, -16, v67
	v_cmp_lt_i32_e64 s[68:69], -1, v67
	v_cvt_f32_u32_e32 v180, v67
	v_cmp_lt_i32_e64 s[70:71], 15, v67
	v_or_b32_e32 v67, 35, v70
	v_sub_u32_e32 v67, v148, v67
	v_cvt_f32_u32_e32 v181, v71
	v_add_u32_e32 v71, -16, v67
	v_cmp_lt_i32_e64 s[72:73], -1, v67
	v_cvt_f32_u32_e32 v182, v67
	v_cmp_lt_i32_e64 s[74:75], 15, v67
	v_or_b32_e32 v67, 64, v70
	v_sub_u32_e32 v67, v148, v67
	v_cvt_f32_u32_e32 v183, v71
	v_add_u32_e32 v71, -16, v67
	v_cmp_lt_i32_e64 s[78:79], -1, v67
	v_cvt_f32_u32_e32 v184, v67
	v_cmp_lt_i32_e64 s[80:81], 15, v67
	v_or_b32_e32 v67, 0x41, v70
	s_add_u32 s34, s4, 0x10802700
	v_sub_u32_e32 v67, v148, v67
	s_addc_u32 s35, s5, 0
	s_lshl_b64 s[4:5], s[0:1], 2
	v_mul_lo_u32 v68, v148, s10
	v_cvt_f32_u32_e32 v185, v71
	v_add_u32_e32 v71, -16, v67
	v_cmp_lt_i32_e64 s[82:83], -1, v67
	v_cvt_f32_u32_e32 v186, v67
	v_cmp_lt_i32_e64 s[84:85], 15, v67
	v_or_b32_e32 v67, 0x42, v70
	s_add_u32 s12, s6, s4
	v_add_u32_e32 v74, 0, v68
	v_lshlrev_b32_e32 v68, 4, v73
	v_sub_u32_e32 v73, v148, v70
	v_sub_u32_e32 v67, v148, v67
	s_addc_u32 s13, s7, s5
	v_cmp_lt_i32_e64 s[4:5], -1, v73
	v_cvt_f32_u32_e32 v187, v71
	v_add_u32_e32 v71, -16, v67
	v_cmp_lt_i32_e64 s[86:87], -1, v67
	v_cvt_f32_u32_e32 v188, v67
	v_cmp_lt_i32_e64 s[88:89], 15, v67
	v_or_b32_e32 v67, 0x43, v70
	v_writelane_b32 v252, s4, 48
	v_sub_u32_e32 v67, v148, v67
	v_cvt_f32_u32_e32 v189, v71
	v_writelane_b32 v252, s5, 49
	v_cmp_lt_i32_e64 s[4:5], 15, v73
	v_add_u32_e32 v71, -16, v67
	v_cmp_lt_i32_e64 s[90:91], -1, v67
	v_cvt_f32_u32_e32 v190, v67
	v_cmp_lt_i32_e64 s[92:93], 15, v67
	v_or_b32_e32 v67, 0x60, v70
	v_writelane_b32 v252, s4, 50
	v_sub_u32_e32 v67, v148, v67
	v_cmp_lt_i32_e64 s[40:41], -1, v69
	v_writelane_b32 v252, s5, 51
	v_cmp_lt_i32_e64 s[58:59], 1, v69
	v_cmp_lt_i32_e64 s[76:77], 3, v69
	v_cmp_lt_i32_e64 s[94:95], 5, v69
	v_add_u32_e32 v69, -16, v67
	v_cmp_lt_i32_e64 s[96:97], -1, v67
	v_cvt_f32_u32_e32 v192, v67
	v_cmp_lt_i32_e64 s[4:5], 15, v67
	v_or_b32_e32 v67, 0x61, v70
	v_add_u32_e32 v75, 1, v148
	v_add_u32_e32 v77, -16, v73
	v_cvt_f32_u32_e32 v151, v73
	v_xad_u32 v73, v70, -1, v148
	v_sub_u32_e32 v67, v148, v67
	v_cvt_f32_i32_e32 v149, v75
	v_add_u32_e32 v75, s9, v68
	v_cvt_f32_u32_e32 v152, v77
	v_add_u32_e32 v77, -16, v73
	v_cmp_lt_i32_e64 s[46:47], -1, v73
	v_cvt_f32_u32_e32 v153, v73
	v_cmp_lt_i32_e64 s[48:49], 15, v73
	v_or_b32_e32 v73, 2, v70
	v_cvt_f32_u32_e32 v193, v69
	v_add_u32_e32 v69, -16, v67
	v_cmp_lt_i32_e64 s[6:7], -1, v67
	v_cvt_f32_u32_e32 v194, v67
	v_cmp_lt_i32_e64 s[8:9], 15, v67
	v_or_b32_e32 v67, 0x62, v70
	v_sub_u32_e32 v73, v148, v73
	v_cvt_f32_u32_e32 v195, v69
	v_sub_u32_e32 v67, v148, v67
	v_mov_b32_e32 v69, v32
	v_cvt_f32_u32_e32 v154, v77
	v_add_u32_e32 v77, -16, v73
	v_cmp_lt_i32_e64 s[50:51], -1, v73
	v_cvt_f32_u32_e32 v155, v73
	v_cmp_lt_i32_e64 s[52:53], 15, v73
	v_or_b32_e32 v73, 3, v70
	v_cvt_f32_u32_e32 v191, v71
	v_add_u32_e32 v71, -16, v67
	v_cmp_lt_i32_e64 s[10:11], -1, v67
	v_cvt_f32_u32_e32 v196, v67
	v_lshl_add_u64 v[128:129], s[12:13], 0, v[68:69]
	v_cmp_lt_i32_e64 s[12:13], 15, v67
	v_or_b32_e32 v67, 0x63, v70
	v_sub_u32_e32 v73, v148, v73
	v_sub_u32_e32 v67, v148, v67
	v_cvt_f32_u32_e32 v156, v77
	v_add_u32_e32 v77, -16, v73
	v_add_u32_e32 v69, -16, v67
	v_cvt_f32_u32_e32 v157, v73
	v_cvt_f32_u32_e32 v158, v77
	v_cvt_f32_u32_e32 v197, v71
	v_cvt_f32_u32_e32 v198, v67
	v_cvt_f32_u32_e32 v199, v69
	v_add3_u32 v150, 0, v76, v68
	v_cmp_lt_i32_e64 s[54:55], -1, v73
	v_cmp_lt_i32_e64 s[56:57], 15, v73
	v_lshlrev_b32_e32 v200, 2, v72
	v_lshlrev_b32_e32 v130, 1, v66
	v_add_u32_e32 v201, v74, v68
	v_add_u32_e32 v220, v75, v76
	v_lshlrev_b32_e32 v132, 1, v70
	v_readlane_b32 s0, v252, 1
	s_mov_b32 s42, s2
	v_cmp_lt_i32_e64 s[14:15], -1, v67
	v_cmp_lt_i32_e64 s[16:17], 15, v67
	s_branch .LBB0_383
